# baseline (speedup 1.0000x reference)
; __device__ __forceinline__ u16 f2bf(float f) { return (u16)(pack2(f, f) & 0xffffu); }
; template <bool MAP>
; __device__ __forceinline__ void transpose_tile(const float* __restrict__ src, int K, int N, u16* __restrict__ dst,
;                                                int kt, int nt, char* smem) {
;     ...
;   __syncthreads();
; #pragma unroll
;   for (int i = 0; i < 4; ++i) {
;     int k = (tid >> 4) + 16 * i;
;     int n4 = (tid & 15) * 4;
;     float4 v = make_float4(0.f, 0.f, 0.f, 0.f);
;     if (n0 + n4 < N) v = *(const float4*)(src + (size_t)(k0 + k) * N + n0 + n4);
;     Ts[(n4 + 0) * 72 + k] = f2bf(v.x);
;     Ts[(n4 + 1) * 72 + k] = f2bf(v.y);
;     Ts[(n4 + 2) * 72 + k] = f2bf(v.z);
;     Ts[(n4 + 3) * 72 + k] = f2bf(v.w);
;   }
;   __syncthreads();
.LBB0_42:
	s_andn2_b64 vcc, exec, s[6:7]
	s_cbranch_vccnz .LBB0_64
	s_add_i32 s4, s83, 0xfe80
	s_and_b32 s6, s4, 0xffff
	s_mulk_i32 s6, 0x7243
	s_lshr_b32 s6, s6, 16
	s_sub_i32 s7, s4, s6
	s_bfe_u32 s7, s7, 0xf0001
	s_add_i32 s7, s7, s6
	s_bfe_u32 s6, s7, 0x90007
	s_mul_i32 s7, s6, 0xb1
	s_sub_i32 s7, s4, s7
	s_lshl_b32 s4, s6, 6
	s_lshl_b32 s6, s7, 6
	v_mov_b32_e32 v1, v216
	s_and_b32 s18, s6, 0xffc0
	s_and_b32 s4, s4, 0x7fc0
	v_lshlrev_b32_e32 v2, 2, v1
	s_lshl_b32 s6, s18, 2
	v_and_b32_e32 v5, 60, v2
	s_add_u32 s6, s44, s6
	v_or_b32_e32 v2, s18, v5
	s_addc_u32 s7, s45, 0
	v_lshlrev_b32_e32 v10, 2, v5
	v_ashrrev_i32_e32 v4, 4, v1
	v_cmp_gt_u32_e32 vcc, s62, v2
	v_lshl_add_u64 v[2:3], s[6:7], 0, v[10:11]
	v_mov_b32_e32 v6, 0
	v_mov_b32_e32 v7, 0
	v_mov_b32_e32 v8, 0
	v_mov_b32_e32 v9, 0
	v_mov_b32_e32 v10, 0
	s_barrier
	v_mov_b32_e32 v140, 0
	v_mov_b32_e32 v141, 0
	v_mov_b32_e32 v142, 0
	v_mov_b32_e32 v143, 0
	v_mov_b32_e32 v144, 0
	v_mov_b32_e32 v145, 0
	v_mov_b32_e32 v146, 0
	v_mov_b32_e32 v147, 0
	v_mov_b32_e32 v148, 0
	v_mov_b32_e32 v149, 0
	v_mov_b32_e32 v150, 0
	v_mov_b32_e32 v151, 0
	v_mov_b32_e32 v152, 0
	v_mov_b32_e32 v153, 0
	v_mov_b32_e32 v154, 0
	v_mov_b32_e32 v155, 0
	s_and_saveexec_b64 s[6:7], vcc
	s_cbranch_execz .Lprep_tt_skip
	v_add_u32_e32 v7, s4, v4
	v_mad_i64_i32 v[8:9], s[20:21], v7, s63, v[2:3]
	global_load_dwordx4 v[140:143], v[8:9], off
	v_add3_u32 v7, v4, s4, 16
	v_mad_i64_i32 v[8:9], s[20:21], v7, s63, v[2:3]
	global_load_dwordx4 v[144:147], v[8:9], off
	v_add3_u32 v7, v4, s4, 32
	v_mad_i64_i32 v[8:9], s[20:21], v7, s63, v[2:3]
	global_load_dwordx4 v[148:151], v[8:9], off
	v_add3_u32 v7, v4, s4, 48
	v_mad_i64_i32 v[8:9], s[20:21], v7, s63, v[2:3]
	global_load_dwordx4 v[152:155], v[8:9], off
	s_waitcnt vmcnt(0)
	v_cvt_pk_bf16_f32 v140, v140, s0
	v_cvt_pk_bf16_f32 v141, v141, s0
	v_cvt_pk_bf16_f32 v142, v142, s0
	v_cvt_pk_bf16_f32 v143, v143, s0
	v_cvt_pk_bf16_f32 v144, v144, s0
	v_cvt_pk_bf16_f32 v145, v145, s0
	v_cvt_pk_bf16_f32 v146, v146, s0
	v_cvt_pk_bf16_f32 v147, v147, s0
	v_cvt_pk_bf16_f32 v148, v148, s0
	v_cvt_pk_bf16_f32 v149, v149, s0
	v_cvt_pk_bf16_f32 v150, v150, s0
	v_cvt_pk_bf16_f32 v151, v151, s0
	v_cvt_pk_bf16_f32 v152, v152, s0
	v_cvt_pk_bf16_f32 v153, v153, s0
	v_cvt_pk_bf16_f32 v154, v154, s0
	v_cvt_pk_bf16_f32 v155, v155, s0
.Lprep_tt_skip:
	s_or_b64 exec, exec, s[6:7]
	v_lshlrev_b32_e32 v12, 1, v4
	v_mad_u32_u24 v5, v5, s60, v12
	ds_write_b16 v5, v140
	ds_write_b16 v5, v141 offset:144
	ds_write_b16 v5, v142 offset:288
	ds_write_b16 v5, v143 offset:432
	ds_write_b16 v5, v144 offset:32
	ds_write_b16 v5, v145 offset:176
	ds_write_b16 v5, v146 offset:320
	ds_write_b16 v5, v147 offset:464
	ds_write_b16 v5, v148 offset:64
	ds_write_b16 v5, v149 offset:208
	ds_write_b16 v5, v150 offset:352
	ds_write_b16 v5, v151 offset:496
	ds_write_b16 v5, v152 offset:96
	ds_write_b16 v5, v153 offset:240
	ds_write_b16 v5, v154 offset:384
	ds_write_b16 v5, v155 offset:528
	v_ashrrev_i32_e32 v3, 2, v1
	v_add_u32_e32 v2, s18, v3
	v_cmp_gt_i32_e32 vcc, s62, v2
	s_waitcnt lgkmcnt(0)
	s_barrier
	s_and_saveexec_b64 s[6:7], vcc
	s_cbranch_execz .LBB0_63
	v_cmp_lt_i32_e32 vcc, s64, v2
	s_and_saveexec_b64 s[18:19], vcc
	s_cbranch_execz .LBB0_62
	v_cmp_lt_u32_e32 vcc, s65, v2
	s_and_saveexec_b64 s[20:21], vcc
	s_xor_b64 s[20:21], exec, s[20:21]
	s_cbranch_execz .LBB0_59
	v_cmp_lt_u32_e32 vcc, s66, v2
	s_and_saveexec_b64 s[22:23], vcc
	s_xor_b64 s[22:23], exec, s[22:23]
	v_add_u32_e32 v2, -16, v2
	s_andn2_saveexec_b64 s[22:23], s[22:23]
	v_or_b32_e32 v2, 0x2000, v2
	s_or_b64 exec, exec, s[22:23]
